# deferred weight-transpose hooks claim more items per idle workgroup (units 3->8,8,5,5) on top of epilogue re-sync
# speedup vs baseline: 1.0192x; 1.0049x over previous
; #define LAS __attribute__((address_space(3)))
; __device__ __forceinline__ int get_tid() { int t = threadIdx.x; asm volatile("" : "+v"(t)); return t; }
; __device__ __forceinline__ int get_bid() { int b = blockIdx.x; asm volatile("" : "+s"(b)); return b; }
; __device__ __forceinline__ void deferred_work(const Params& P, LAS unsigned char* lds, int maxclaims, int units, int limit_items) {
;     const int tid = get_tid(), wave = tid >> 6, lane = tid & 63;
;     unsigned char* ws = P.ws;
;     LAS float* scr = (LAS float*)(lds + wave * 8448); volatile LAS int* sc = (volatile LAS int*)(lds + 8 * 8448);
;     unsigned* ctr = (unsigned*)(ws + O_BAR) + 3600;
;     for (int n = 0; n < maxclaims; ++n) {
;         __syncthreads();
;         if (tid == 0) { int c = -1; const unsigned cur = __hip_atomic_load(ctr, __ATOMIC_RELAXED, __HIP_MEMORY_SCOPE_AGENT);
;             const int stop = limit_items > 0 ? limit_items : TR_DEF;
;             if ((int)cur * DCH < stop) c = (int)atomicAdd(ctr, (unsigned)units);
;             *sc = c; }
;         __syncthreads();
; __global__ void __launch_bounds__(NTHR, 2) mega_fwd(Params P) {
;     ...
;                 if (DEFER && DEFER_HOOKS && rep == 0 && ph == 15) { const int rem = (S.T * S.nN) % (int)gridDim.x; if (rem != 0 && get_bid() >= rem) deferred_work(P, lds, 1, 3, 0); } } break;
.LBB0_520:
	v_readlane_b32 s0, v253, 22
	v_readlane_b32 s1, v253, 23
	v_readlane_b32 s52, v253, 11
	v_readlane_b32 s70, v253, 15
	v_readlane_b32 s60, v253, 19
	s_andn2_b64 vcc, exec, s[0:1]
	v_readlane_b32 s83, v253, 4
	v_readlane_b32 s84, v253, 5
	v_readlane_b32 s53, v253, 12
	v_readlane_b32 s71, v253, 16
	v_readlane_b32 s61, v253, 20
	s_mov_b32 s95, 0x92492493
	s_movk_i32 s48, 0x7000
	s_cbranch_vccnz .LBB0_561
	s_waitcnt lgkmcnt(0)
	s_abs_i32 s0, s79
	v_cvt_f32_u32_e32 v0, s0
	s_sub_i32 s3, 0, s0
	s_abs_i32 s2, s78
	s_ashr_i32 s1, s78, 31
	v_rcp_iflag_f32_e32 v0, v0
	s_nop 0
	v_mul_f32_e32 v0, 0x4f7ffffe, v0
	v_cvt_u32_f32_e32 v0, v0
	s_nop 0
	v_readfirstlane_b32 s4, v0
	s_mul_i32 s3, s3, s4
	s_mul_hi_u32 s3, s4, s3
	s_add_i32 s4, s4, s3
	s_mul_hi_u32 s3, s2, s4
	s_mul_i32 s3, s3, s0
	s_sub_i32 s2, s2, s3
	s_sub_i32 s3, s2, s0
	s_cmp_ge_u32 s2, s0
	s_cselect_b32 s2, s3, s2
	s_sub_i32 s3, s2, s0
	s_cmp_ge_u32 s2, s0
	s_cselect_b32 s0, s3, s2
	s_xor_b32 s0, s0, s1
	s_sub_i32 s0, s0, s1
	s_cmp_eq_u32 s0, 0
	s_cbranch_scc1 .LBB0_561
	s_mov_b32 s1, s74
	s_cmp_lt_i32 s1, s0
	s_cbranch_scc1 .LBB0_561
	v_mov_b32_e32 v14, v196
	s_waitcnt vmcnt(0)
	v_cmp_eq_u32_e32 vcc, 0, v14
	s_barrier
	s_and_saveexec_b64 s[0:1], vcc
	v_readlane_b32 s10, v253, 9
	v_readlane_b32 s11, v253, 10
	s_cbranch_execz .LBB0_529
	s_nop 3
	global_load_dword v2, v1, s[10:11] sc1
	s_movk_i32 s2, 0x179f
	v_mov_b32_e32 v0, -1
	s_waitcnt vmcnt(0)
	v_cmp_lt_i32_e32 vcc, s2, v2
	s_cbranch_vccnz .LBB0_528
	s_mov_b64 s[6:7], exec
	v_mbcnt_lo_u32_b32 v0, s6, 0
	v_mbcnt_hi_u32_b32 v0, s7, v0
	v_cmp_eq_u32_e32 vcc, 0, v0
	s_and_saveexec_b64 s[4:5], vcc
	s_cbranch_execz .LBB0_527
	s_bcnt1_i32_b64 s2, s[6:7]
	s_mul_i32 s2, s2, 8
	v_mov_b32_e32 v2, s2
	global_atomic_add v2, v1, v2, s[10:11] sc0
.LBB0_527:
	s_or_b64 exec, exec, s[4:5]
	s_waitcnt vmcnt(0)
	v_readfirstlane_b32 s2, v2
	s_nop 1
	v_mad_u32_u24 v0, v0, 8, s2

; __device__ __forceinline__ TDesc tr_decode(const Params& P, unsigned char* ws, int it, int deferred) {
;     int r = it;
;     if (deferred) {
;         if (r < TR_WI) return tr_mk(P.ffn_wi + (size_t)1024 * 7168, 1024, 7168, (bf16_t*)(ws + O_FWI) + (size_t)7168 * 1024, 1, r); r -= TR_WI;
;         if (r < TR_WO) return tr_mk(P.ffn_wo + (size_t)3584 * 1024, 3584, 1024, (bf16_t*)(ws + O_FWO) + (size_t)1024 * 3584, 0, r); r -= TR_WO;
;         if (r < 8 * TR_WI) { const int e = 8 + r / TR_WI; return tr_mk(P.moe_wi + (size_t)e * 1024 * 7168, 1024, 7168, (bf16_t*)(ws + O_MWI) + (size_t)e * 7168 * 1024, 1, r % TR_WI); } r -= 8 * TR_WI;
;         { const int e = 8 + r / TR_WO; return tr_mk(P.moe_wo + (size_t)e * 3584 * 1024, 3584, 1024, (bf16_t*)(ws + O_MWO) + (size_t)e * 1024 * 3584, 0, r % TR_WO); }
; __device__ __forceinline__ void deferred_work(const Params& P, LAS unsigned char* lds, int maxclaims, int units, int limit_items) {
;     ...
;         const int c = *sc, base = c * DCH;
;         if (c < 0 || base >= TR_DEF) break;
;         const int cend = base + units * DCH, i1 = cend < TR_DEF ? cend : TR_DEF;
;         int it = base + wave;
;         float v[32]; TDesc cur;
;         if (it < i1) { cur = tr_decode(P, ws, it, 1); tr_load(cur, v, lane); }
;         while (it < i1) {
;             const int nit = it + NWAVE; float w[32]; TDesc nx = cur;
;             if (nit < i1) { nx = tr_decode(P, ws, nit, 1); tr_load(nx, w, lane); }
.LBB0_529:
	s_or_b64 exec, exec, s[0:1]
	v_lshlrev_b32_e32 v0, 3, v14
	v_and_b32_e32 v18, 56, v0
	v_mov_b32_e32 v0, s69
	s_waitcnt lgkmcnt(0)
	s_barrier
	ds_read_b32 v0, v0
	s_movk_i32 s0, 0x179f
	v_bfe_u32 v9, v14, 5, 1
	v_and_b32_e32 v8, 63, v14
	v_mul_u32_u24_e32 v15, 0x84, v9
	s_waitcnt lgkmcnt(0)
	v_cmp_lt_u32_e32 vcc, s0, v0
	v_mul_u32_u24_e32 v10, 0x84, v18
	s_cbranch_vccnz .LBB0_560
	v_lshlrev_b32_e32 v0, 3, v0
	v_ashrrev_i32_e32 v12, 6, v14
	v_min_u32_e32 v2, 0xbcc0, v0
	v_add_u32_e32 v11, 64, v2
	v_add_u32_e32 v16, v0, v12
	v_cmp_lt_i32_e32 vcc, v16, v11
	s_and_saveexec_b64 s[4:5], vcc
	s_cbranch_execz .LBB0_559
	s_movk_i32 s0, 0xdff
	v_cmp_lt_i32_e32 vcc, s0, v16
	s_and_saveexec_b64 s[0:1], vcc
	s_xor_b64 s[0:1], exec, s[0:1]
	s_cbranch_execz .LBB0_541
	v_cmp_lt_u32_e32 vcc, s62, v16
	s_and_saveexec_b64 s[6:7], vcc
	s_xor_b64 s[6:7], exec, s[6:7]
	s_cbranch_execz .LBB0_538
	s_mov_b32 s2, 0x84ff
	v_cmp_lt_u32_e32 vcc, s2, v16
	s_and_saveexec_b64 s[8:9], vcc
	s_xor_b64 s[8:9], exec, s[8:9]
	s_cbranch_execz .LBB0_535
	v_add_u16_e32 v0, 0x7b00, v16
	s_movk_i32 s2, 0x2493
	v_mul_u32_u24_sdwa v13, v0, s2 dst_sel:DWORD dst_unused:UNUSED_PAD src0_sel:BYTE_1 src1_sel:DWORD
	v_add_u16_sdwa v6, v13, v201 dst_sel:DWORD dst_unused:UNUSED_PAD src0_sel:WORD_1 src1_sel:DWORD
	v_mov_b64_e32 v[2:3], s[24:25]
	s_mov_b32 s2, 0xe00000
	v_mad_u64_u32 v[2:3], s[10:11], v6, s2, v[2:3]
	v_mov_b64_e32 v[4:5], s[52:53]
	s_mov_b32 s2, 0x700000
	v_mad_u64_u32 v[6:7], s[10:11], v6, s2, v[4:5]
	s_movk_i32 s2, 0x700
	v_mul_lo_u16_sdwa v4, v13, s2 dst_sel:DWORD dst_unused:UNUSED_PAD src0_sel:WORD_1 src1_sel:DWORD
	v_sub_u16_e32 v0, v0, v4
	v_lshlrev_b16_e32 v4, 5, v0
	v_lshlrev_b16_e32 v0, 1, v0
	v_and_b32_e32 v4, 0x3e0, v4
	v_and_b32_e32 v13, 0xfc0, v0
	v_lshlrev_b32_sdwa v0, v202, v13 dst_sel:DWORD dst_unused:UNUSED_PAD src0_sel:DWORD src1_sel:WORD_0
	v_and_b32_e32 v17, 0xffff, v4
	v_lshl_add_u64 v[2:3], v[2:3], 0, v[0:1]
	v_lshlrev_b32_e32 v0, 2, v17
	s_movk_i32 s2, 0x1c00
	v_lshl_add_u64 v[4:5], v[2:3], 0, v[0:1]
	v_mad_u64_u32 v[2:3], s[10:11], v17, s2, v[6:7]
	v_lshlrev_b32_sdwa v0, v200, v13 dst_sel:DWORD dst_unused:UNUSED_PAD src0_sel:DWORD src1_sel:WORD_0
	v_lshl_add_u64 v[2:3], v[2:3], 0, v[0:1]

; __device__ __forceinline__ int get_bid() { int b = blockIdx.x; asm volatile("" : "+s"(b)); return b; }
; __device__ __forceinline__ void deferred_work(const Params& P, LAS unsigned char* lds, int maxclaims, int units, int limit_items) {
;     ...
;     for (int n = 0; n < maxclaims; ++n) {
;         __syncthreads();
;         if (tid == 0) { int c = -1; const unsigned cur = __hip_atomic_load(ctr, __ATOMIC_RELAXED, __HIP_MEMORY_SCOPE_AGENT);
;             const int stop = limit_items > 0 ? limit_items : TR_DEF;
;             if ((int)cur * DCH < stop) c = (int)atomicAdd(ctr, (unsigned)units);
;             *sc = c; }
; __global__ void __launch_bounds__(NTHR, 2) mega_fwd(Params P) {
;     ...
;                 if (DEFER && DEFER_HOOKS && rep == 0 && a0 == 1) { const int b = get_bid(); if (b >= 69 && !(b >= 128 && b < 193)) deferred_work(P, lds, 1, 3, 0); } } break;
.LBB0_766:
	v_readlane_b32 s0, v253, 40
	v_readlane_b32 s1, v253, 41
	s_andn2_b64 vcc, exec, s[0:1]
	s_cbranch_vccnz .LBB0_806
	s_mov_b32 s2, s74
	s_cmpk_lt_i32 s2, 0x45
	s_cselect_b64 s[0:1], -1, 0
	s_addk_i32 s2, 0xff80
	s_cmpk_lt_u32 s2, 0x41
	s_cselect_b64 s[4:5], -1, 0
	s_or_b64 s[0:1], s[0:1], s[4:5]
	s_and_b64 vcc, exec, s[0:1]
	s_cbranch_vccnz .LBB0_806
	v_mov_b32_e32 v14, v196
	s_waitcnt vmcnt(0) lgkmcnt(0)
	v_cmp_eq_u32_e32 vcc, 0, v14
	s_barrier
	s_and_saveexec_b64 s[0:1], vcc
	s_cbranch_execz .LBB0_774
	global_load_dword v2, v1, s[72:73] sc1
	s_movk_i32 s2, 0x179f
	v_mov_b32_e32 v0, -1
	s_waitcnt vmcnt(0)
	v_cmp_lt_i32_e32 vcc, s2, v2
	s_cbranch_vccnz .LBB0_773
	s_mov_b64 s[6:7], exec
	v_mbcnt_lo_u32_b32 v0, s6, 0
	v_mbcnt_hi_u32_b32 v0, s7, v0
	v_cmp_eq_u32_e32 vcc, 0, v0
	s_and_saveexec_b64 s[4:5], vcc
	s_cbranch_execz .LBB0_772
	s_bcnt1_i32_b64 s2, s[6:7]
	s_mul_i32 s2, s2, 8
	v_mov_b32_e32 v2, s2
	global_atomic_add v2, v1, v2, s[72:73] sc0

; __device__ __forceinline__ int get_bid() { int b = blockIdx.x; asm volatile("" : "+s"(b)); return b; }
; __device__ __forceinline__ void deferred_work(const Params& P, LAS unsigned char* lds, int maxclaims, int units, int limit_items) {
;     ...
;     for (int n = 0; n < maxclaims; ++n) {
;         __syncthreads();
;         if (tid == 0) { int c = -1; const unsigned cur = __hip_atomic_load(ctr, __ATOMIC_RELAXED, __HIP_MEMORY_SCOPE_AGENT);
;             const int stop = limit_items > 0 ? limit_items : TR_DEF;
;             if ((int)cur * DCH < stop) c = (int)atomicAdd(ctr, (unsigned)units);
;             *sc = c; }
; __global__ void __launch_bounds__(NTHR, 2) mega_fwd(Params P) {
;     ...
;                 if (DEFER && DEFER_HOOKS && rep == 0 && ph == 6 && get_bid() >= (S.nwg % (int)gridDim.x)) deferred_work(P, lds, 1, 3, 0); } break;
.LBB0_886:
	v_readlane_b32 s0, v253, 26
	v_readlane_b32 s1, v253, 27
	s_andn2_b64 vcc, exec, s[0:1]
	s_cbranch_vccnz .LBB0_926
	s_abs_i32 s0, s34
	v_cvt_f32_u32_e32 v0, s0
	s_sub_i32 s2, 0, s0
	s_mov_b32 s1, s74
	v_rcp_iflag_f32_e32 v0, v0
	s_nop 0
	v_mul_f32_e32 v0, 0x4f7ffffe, v0
	v_cvt_u32_f32_e32 v0, v0
	s_nop 0
	v_readfirstlane_b32 s3, v0
	s_mul_i32 s2, s2, s3
	s_mul_hi_u32 s2, s3, s2
	s_add_i32 s3, s3, s2
	s_mul_hi_u32 s2, s30, s3
	s_mul_i32 s2, s2, s0
	s_sub_i32 s2, s30, s2
	s_sub_i32 s3, s2, s0
	s_cmp_ge_u32 s2, s0
	s_cselect_b32 s2, s3, s2
	s_sub_i32 s3, s2, s0
	s_cmp_ge_u32 s2, s0
	s_cselect_b32 s0, s3, s2
	s_cmp_lt_i32 s1, s0
	s_cbranch_scc1 .LBB0_926
	v_mov_b32_e32 v14, v196
	s_waitcnt vmcnt(0) lgkmcnt(0)
	v_cmp_eq_u32_e32 vcc, 0, v14
	s_barrier
	s_and_saveexec_b64 s[0:1], vcc
	s_cbranch_execz .LBB0_894
	global_load_dword v2, v1, s[72:73] sc1
	s_movk_i32 s2, 0x179f
	v_mov_b32_e32 v0, -1
	s_waitcnt vmcnt(0)
	v_cmp_lt_i32_e32 vcc, s2, v2
	s_cbranch_vccnz .LBB0_893
	s_mov_b64 s[6:7], exec
	v_mbcnt_lo_u32_b32 v0, s6, 0
	v_mbcnt_hi_u32_b32 v0, s7, v0
	v_cmp_eq_u32_e32 vcc, 0, v0
	s_and_saveexec_b64 s[4:5], vcc
	s_cbranch_execz .LBB0_892
	s_bcnt1_i32_b64 s2, s[6:7]
	s_mul_i32 s2, s2, 5
	v_mov_b32_e32 v2, s2
	global_atomic_add v2, v1, v2, s[72:73] sc0
.LBB0_892:
	s_or_b64 exec, exec, s[4:5]
	s_waitcnt vmcnt(0)
	v_readfirstlane_b32 s2, v2
	s_nop 1
	v_mad_u32_u24 v0, v0, 5, s2

; __device__ __forceinline__ TDesc tr_decode(const Params& P, unsigned char* ws, int it, int deferred) {
;     int r = it;
;     if (deferred) {
;         if (r < TR_WI) return tr_mk(P.ffn_wi + (size_t)1024 * 7168, 1024, 7168, (bf16_t*)(ws + O_FWI) + (size_t)7168 * 1024, 1, r); r -= TR_WI;
;         if (r < TR_WO) return tr_mk(P.ffn_wo + (size_t)3584 * 1024, 3584, 1024, (bf16_t*)(ws + O_FWO) + (size_t)1024 * 3584, 0, r); r -= TR_WO;
;         if (r < 8 * TR_WI) { const int e = 8 + r / TR_WI; return tr_mk(P.moe_wi + (size_t)e * 1024 * 7168, 1024, 7168, (bf16_t*)(ws + O_MWI) + (size_t)e * 7168 * 1024, 1, r % TR_WI); } r -= 8 * TR_WI;
;         { const int e = 8 + r / TR_WO; return tr_mk(P.moe_wo + (size_t)e * 3584 * 1024, 3584, 1024, (bf16_t*)(ws + O_MWO) + (size_t)e * 1024 * 3584, 0, r % TR_WO); }
; __device__ __forceinline__ void deferred_work(const Params& P, LAS unsigned char* lds, int maxclaims, int units, int limit_items) {
;     ...
;         const int c = *sc, base = c * DCH;
;         if (c < 0 || base >= TR_DEF) break;
;         const int cend = base + units * DCH, i1 = cend < TR_DEF ? cend : TR_DEF;
;         int it = base + wave;
;         float v[32]; TDesc cur;
;         if (it < i1) { cur = tr_decode(P, ws, it, 1); tr_load(cur, v, lane); }
;         while (it < i1) {
;             const int nit = it + NWAVE; float w[32]; TDesc nx = cur;
;             if (nit < i1) { nx = tr_decode(P, ws, nit, 1); tr_load(nx, w, lane); }
.LBB0_894:
	s_or_b64 exec, exec, s[0:1]
	v_lshlrev_b32_e32 v0, 3, v14
	v_and_b32_e32 v18, 56, v0
	v_mov_b32_e32 v0, s69
	s_waitcnt lgkmcnt(0)
	s_barrier
	ds_read_b32 v0, v0
	s_movk_i32 s0, 0x179f
	v_bfe_u32 v9, v14, 5, 1
	v_and_b32_e32 v8, 63, v14
	v_mul_u32_u24_e32 v15, 0x84, v9
	s_waitcnt lgkmcnt(0)
	v_cmp_lt_u32_e32 vcc, s0, v0
	v_mul_u32_u24_e32 v10, 0x84, v18
	s_cbranch_vccnz .LBB0_925
	v_lshlrev_b32_e32 v0, 3, v0
	v_ashrrev_i32_e32 v12, 6, v14
	v_min_u32_e32 v2, 0xbcd8, v0
	v_add_u32_e32 v11, 40, v2
	v_add_u32_e32 v16, v0, v12
	v_cmp_lt_i32_e32 vcc, v16, v11
	s_and_saveexec_b64 s[4:5], vcc
	s_cbranch_execz .LBB0_924
	s_movk_i32 s0, 0xdff
	v_cmp_lt_i32_e32 vcc, s0, v16
	s_and_saveexec_b64 s[0:1], vcc
	s_xor_b64 s[0:1], exec, s[0:1]
	s_cbranch_execz .LBB0_906
	v_cmp_lt_u32_e32 vcc, s62, v16
	s_and_saveexec_b64 s[6:7], vcc
	s_xor_b64 s[6:7], exec, s[6:7]
	s_cbranch_execz .LBB0_903
	s_mov_b32 s2, 0x84ff
	v_cmp_lt_u32_e32 vcc, s2, v16
	s_and_saveexec_b64 s[8:9], vcc
	s_xor_b64 s[8:9], exec, s[8:9]
	s_cbranch_execz .LBB0_900
	v_add_u16_e32 v0, 0x7b00, v16
	s_movk_i32 s2, 0x2493
	v_mul_u32_u24_sdwa v13, v0, s2 dst_sel:DWORD dst_unused:UNUSED_PAD src0_sel:BYTE_1 src1_sel:DWORD
	v_add_u16_sdwa v6, v13, v201 dst_sel:DWORD dst_unused:UNUSED_PAD src0_sel:WORD_1 src1_sel:DWORD
	v_mov_b64_e32 v[2:3], s[24:25]
	s_mov_b32 s2, 0xe00000
	v_mad_u64_u32 v[2:3], s[10:11], v6, s2, v[2:3]
	v_mov_b64_e32 v[4:5], s[52:53]
	s_mov_b32 s2, 0x700000
	v_mad_u64_u32 v[6:7], s[10:11], v6, s2, v[4:5]
	s_movk_i32 s2, 0x700
	v_mul_lo_u16_sdwa v4, v13, s2 dst_sel:DWORD dst_unused:UNUSED_PAD src0_sel:WORD_1 src1_sel:DWORD
	v_sub_u16_e32 v0, v0, v4
	v_lshlrev_b16_e32 v4, 5, v0
	v_lshlrev_b16_e32 v0, 1, v0
	v_and_b32_e32 v4, 0x3e0, v4
	v_and_b32_e32 v13, 0xfc0, v0
	v_lshlrev_b32_sdwa v0, v202, v13 dst_sel:DWORD dst_unused:UNUSED_PAD src0_sel:DWORD src1_sel:WORD_0
	v_and_b32_e32 v17, 0xffff, v4
	v_lshl_add_u64 v[2:3], v[2:3], 0, v[0:1]
	v_lshlrev_b32_e32 v0, 2, v17
	s_movk_i32 s2, 0x1c00
	v_lshl_add_u64 v[4:5], v[2:3], 0, v[0:1]
	v_mad_u64_u32 v[2:3], s[10:11], v17, s2, v[6:7]
	v_lshlrev_b32_sdwa v0, v200, v13 dst_sel:DWORD dst_unused:UNUSED_PAD src0_sel:DWORD src1_sel:WORD_0
	v_lshl_add_u64 v[2:3], v[2:3], 0, v[0:1]

; __device__ __forceinline__ int get_bid() { int b = blockIdx.x; asm volatile("" : "+s"(b)); return b; }
; __device__ __forceinline__ void deferred_work(const Params& P, LAS unsigned char* lds, int maxclaims, int units, int limit_items) {
;     ...
;     for (int n = 0; n < maxclaims; ++n) {
;         __syncthreads();
;         if (tid == 0) { int c = -1; const unsigned cur = __hip_atomic_load(ctr, __ATOMIC_RELAXED, __HIP_MEMORY_SCOPE_AGENT);
;             const int stop = limit_items > 0 ? limit_items : TR_DEF;
;             if ((int)cur * DCH < stop) c = (int)atomicAdd(ctr, (unsigned)units);
;             *sc = c; }
; __global__ void __launch_bounds__(NTHR, 2) mega_fwd(Params P) {
;     ...
;                 if (DEFER && DEFER_HOOKS && rep == 0 && ph == 2 && get_bid() >= (S.nwg % (int)gridDim.x)) deferred_work(P, lds, 1, 3, 0); } break;
.LBB0_1037:
	v_readlane_b32 s0, v253, 32
	v_readlane_b32 s1, v253, 33
	s_andn2_b64 vcc, exec, s[0:1]
	s_cbranch_vccnz .LBB0_1077
	s_abs_i32 s0, s21
	v_cvt_f32_u32_e32 v0, s0
	s_sub_i32 s2, 0, s0
	s_mov_b32 s1, s74
	v_rcp_iflag_f32_e32 v0, v0
	s_nop 0
	v_mul_f32_e32 v0, 0x4f7ffffe, v0
	v_cvt_u32_f32_e32 v0, v0
	s_nop 0
	v_readfirstlane_b32 s3, v0
	s_mul_i32 s2, s2, s3
	s_mul_hi_u32 s2, s3, s2
	s_add_i32 s3, s3, s2
	s_mul_hi_u32 s2, s20, s3
	s_mul_i32 s2, s2, s0
	s_sub_i32 s2, s20, s2
	s_sub_i32 s3, s2, s0
	s_cmp_ge_u32 s2, s0
	s_cselect_b32 s2, s3, s2
	s_sub_i32 s3, s2, s0
	s_cmp_ge_u32 s2, s0
	s_cselect_b32 s0, s3, s2
	s_cmp_lt_i32 s1, s0
	s_cbranch_scc1 .LBB0_1077
	v_mov_b32_e32 v14, v196
	s_waitcnt vmcnt(0) lgkmcnt(0)
	v_cmp_eq_u32_e32 vcc, 0, v14
	s_barrier
	s_and_saveexec_b64 s[0:1], vcc
	s_cbranch_execz .LBB0_1045
	global_load_dword v2, v1, s[72:73] sc1
	s_movk_i32 s2, 0x179f
	v_mov_b32_e32 v0, -1
	s_waitcnt vmcnt(0)
	v_cmp_lt_i32_e32 vcc, s2, v2
	s_cbranch_vccnz .LBB0_1044
	s_mov_b64 s[6:7], exec
	v_mbcnt_lo_u32_b32 v0, s6, 0
	v_mbcnt_hi_u32_b32 v0, s7, v0
	v_cmp_eq_u32_e32 vcc, 0, v0
	s_and_saveexec_b64 s[4:5], vcc
	s_cbranch_execz .LBB0_1043
	s_bcnt1_i32_b64 s2, s[6:7]
	s_mul_i32 s2, s2, 5
	v_mov_b32_e32 v2, s2
	global_atomic_add v2, v1, v2, s[72:73] sc0

; __device__ __forceinline__ TDesc tr_decode(const Params& P, unsigned char* ws, int it, int deferred) {
;     int r = it;
;     if (deferred) {
;         if (r < TR_WI) return tr_mk(P.ffn_wi + (size_t)1024 * 7168, 1024, 7168, (bf16_t*)(ws + O_FWI) + (size_t)7168 * 1024, 1, r); r -= TR_WI;
;         if (r < TR_WO) return tr_mk(P.ffn_wo + (size_t)3584 * 1024, 3584, 1024, (bf16_t*)(ws + O_FWO) + (size_t)1024 * 3584, 0, r); r -= TR_WO;
;         if (r < 8 * TR_WI) { const int e = 8 + r / TR_WI; return tr_mk(P.moe_wi + (size_t)e * 1024 * 7168, 1024, 7168, (bf16_t*)(ws + O_MWI) + (size_t)e * 7168 * 1024, 1, r % TR_WI); } r -= 8 * TR_WI;
;         { const int e = 8 + r / TR_WO; return tr_mk(P.moe_wo + (size_t)e * 3584 * 1024, 3584, 1024, (bf16_t*)(ws + O_MWO) + (size_t)e * 1024 * 3584, 0, r % TR_WO); }
; __device__ __forceinline__ void deferred_work(const Params& P, LAS unsigned char* lds, int maxclaims, int units, int limit_items) {
;     ...
;         const int c = *sc, base = c * DCH;
;         if (c < 0 || base >= TR_DEF) break;
;         const int cend = base + units * DCH, i1 = cend < TR_DEF ? cend : TR_DEF;
;         int it = base + wave;
;         float v[32]; TDesc cur;
;         if (it < i1) { cur = tr_decode(P, ws, it, 1); tr_load(cur, v, lane); }
;         while (it < i1) {
;             const int nit = it + NWAVE; float w[32]; TDesc nx = cur;
;             if (nit < i1) { nx = tr_decode(P, ws, nit, 1); tr_load(nx, w, lane); }
.LBB0_1045:
	s_or_b64 exec, exec, s[0:1]
	v_lshlrev_b32_e32 v0, 3, v14
	v_and_b32_e32 v18, 56, v0
	v_mov_b32_e32 v0, s69
	s_waitcnt lgkmcnt(0)
	s_barrier
	ds_read_b32 v0, v0
	s_movk_i32 s0, 0x179f
	v_bfe_u32 v9, v14, 5, 1
	v_and_b32_e32 v8, 63, v14
	v_mul_u32_u24_e32 v15, 0x84, v9
	s_waitcnt lgkmcnt(0)
	v_cmp_lt_u32_e32 vcc, s0, v0
	v_mul_u32_u24_e32 v10, 0x84, v18
	s_movk_i32 s20, 0xdf7
	s_cbranch_vccnz .LBB0_1076
	v_lshlrev_b32_e32 v0, 3, v0
	v_ashrrev_i32_e32 v12, 6, v14
	v_min_u32_e32 v2, 0xbcd8, v0
	v_add_u32_e32 v11, 40, v2
	v_add_u32_e32 v16, v0, v12
	v_cmp_lt_i32_e32 vcc, v16, v11
	s_and_saveexec_b64 s[4:5], vcc
	s_cbranch_execz .LBB0_1075
	s_movk_i32 s0, 0xdff
	v_cmp_lt_i32_e32 vcc, s0, v16
	s_and_saveexec_b64 s[0:1], vcc
	s_xor_b64 s[0:1], exec, s[0:1]
	s_cbranch_execz .LBB0_1057
	v_cmp_lt_u32_e32 vcc, s62, v16
	s_and_saveexec_b64 s[6:7], vcc
	s_xor_b64 s[6:7], exec, s[6:7]
	s_cbranch_execz .LBB0_1054
	s_mov_b32 s2, 0x84ff
	v_cmp_lt_u32_e32 vcc, s2, v16
	s_and_saveexec_b64 s[8:9], vcc
	s_xor_b64 s[8:9], exec, s[8:9]
	s_cbranch_execz .LBB0_1051
	v_add_u16_e32 v0, 0x7b00, v16
	s_movk_i32 s2, 0x2493
	v_mul_u32_u24_sdwa v13, v0, s2 dst_sel:DWORD dst_unused:UNUSED_PAD src0_sel:BYTE_1 src1_sel:DWORD
	v_add_u16_sdwa v6, v13, v201 dst_sel:DWORD dst_unused:UNUSED_PAD src0_sel:WORD_1 src1_sel:DWORD
	v_mov_b64_e32 v[2:3], s[24:25]
	s_mov_b32 s2, 0xe00000
	v_mad_u64_u32 v[2:3], s[10:11], v6, s2, v[2:3]
	v_mov_b64_e32 v[4:5], s[52:53]
	s_mov_b32 s2, 0x700000
	v_mad_u64_u32 v[6:7], s[10:11], v6, s2, v[4:5]
	s_movk_i32 s2, 0x700
	v_mul_lo_u16_sdwa v4, v13, s2 dst_sel:DWORD dst_unused:UNUSED_PAD src0_sel:WORD_1 src1_sel:DWORD
	v_sub_u16_e32 v0, v0, v4
	v_lshlrev_b16_e32 v4, 5, v0
	v_lshlrev_b16_e32 v0, 1, v0
	v_and_b32_e32 v4, 0x3e0, v4
	v_and_b32_e32 v13, 0xfc0, v0
	v_lshlrev_b32_sdwa v0, v202, v13 dst_sel:DWORD dst_unused:UNUSED_PAD src0_sel:DWORD src1_sel:WORD_0
	v_and_b32_e32 v17, 0xffff, v4
	v_lshl_add_u64 v[2:3], v[2:3], 0, v[0:1]
	v_lshlrev_b32_e32 v0, 2, v17
	s_movk_i32 s2, 0x1c00
	v_lshl_add_u64 v[4:5], v[2:3], 0, v[0:1]
	v_mad_u64_u32 v[2:3], s[10:11], v17, s2, v[6:7]
	v_lshlrev_b32_sdwa v0, v200, v13 dst_sel:DWORD dst_unused:UNUSED_PAD src0_sel:DWORD src1_sel:WORD_0
	v_lshl_add_u64 v[2:3], v[2:3], 0, v[0:1]
